# attention phase: one static s_setprio 1 for waves 4-7 (the second wave of each SIMD), reset to 0 at phase exit
# speedup vs baseline: 1.0067x; 1.0067x over previous
.LBB0_786:
	s_andn2_b64 vcc, exec, s[4:5]
	s_cbranch_vccnz .LBB0_856
	v_readlane_b32 s4, v254, 0
	v_readlane_b32 s5, v254, 1
	s_load_dwordx4 s[36:39], s[4:5], 0xb8
	v_readlane_b32 s4, v253, 32
	v_readlane_b32 s5, v253, 33
	s_mov_b32 s7, s5
	v_readlane_b32 s4, v253, 36
	s_waitcnt lgkmcnt(0)
	s_add_u32 s62, s36, 0x3cb2000
	s_addc_u32 s63, s37, 0
	s_add_u32 s70, s38, 0x11139000
	s_addc_u32 s71, s39, 0
	s_add_u32 s88, s38, 0x131b9000
	s_addc_u32 s89, s39, 0
	s_add_u32 s54, s38, 0x8f21000
	s_addc_u32 s55, s39, 0
	v_readlane_b32 s5, v253, 37
	s_add_u32 s44, s38, 0xf0b1000
	s_mov_b32 s5, s7
	s_addc_u32 s45, s39, 0
	s_lshl_b32 s6, s4, 4
	v_writelane_b32 v253, s4, 32
	v_mov_b32_e32 v127, v192
	v_mov_b32_e32 v125, v173
	v_writelane_b32 v253, s5, 33
	s_lshl_b64 s[4:5], s[6:7], 2
	s_add_u32 s4, s38, s4
	v_ashrrev_i32_e32 v122, 3, v127
	s_addc_u32 s5, s39, s5
	v_max_i32_e32 v0, 48, v122
	v_writelane_b32 v253, s4, 38
	v_readfirstlane_b32 s0, v127
	v_subrev_u32_e32 v124, 48, v0
	v_lshlrev_b32_e32 v0, 3, v127
	v_and_b32_e32 v154, 63, v127
	v_writelane_b32 v253, s5, 39
	v_bfe_u32 v1, v127, 4, 2
	s_ashr_i32 s0, s0, 1
	v_and_b32_e32 v172, 48, v127
	v_and_b32_e32 v126, 56, v0
	s_movk_i32 s4, 0x48
	v_and_b32_e32 v155, 15, v127
	s_and_b32 s85, s0, 0xffffffe0
	v_lshlrev_b32_e32 v157, 3, v1
	v_lshl_add_u64 v[120:121], s[54:55], 0, v[172:173]
	v_max_u32_e32 v0, 48, v126
	v_max_u32_e32 v2, 48, v154
	v_mul_lo_u32 v3, v122, s4
	v_lshlrev_b32_e32 v158, 2, v1
	v_lshlrev_b32_e32 v1, 2, v154
	v_lshlrev_b32_e32 v172, 1, v126
	v_cmp_eq_u32_e32 vcc, 0, v127
	v_or_b32_e32 v156, s85, v155
	v_ashrrev_i32_e32 v123, 31, v122
	v_cmp_gt_i32_e64 s[4:5], 64, v127
	s_or_b32 s93, s0, 31
	v_mul_u32_u24_e32 v159, 0x48, v155
	v_xor_b32_e32 v160, 64, v1
	v_xor_b32_e32 v161, 0x80, v1
	v_lshl_add_u64 v[128:129], s[70:71], 0, v[172:173]
	v_sub_u32_e32 v162, 0, v157
	s_mov_b64 s[66:67], 0
	v_lshlrev_b32_e32 v130, 1, v0
	v_lshlrev_b32_e32 v132, 2, v2
	v_lshlrev_b32_e32 v163, 1, v3
	v_readfirstlane_b32 s100, v192
	s_nop 3
	s_lshr_b32 s100, s100, 6
	s_cmp_ge_u32 s100, 4
	s_cbranch_scc0 .Lattn_prio_done
	s_setprio 1
.Lattn_prio_done:
	s_branch .LBB0_790

.LBB0_831:
	s_or_b64 exec, exec, s[66:67]
	s_setprio 0
	v_readlane_b32 s4, v254, 4
	s_add_i32 s0, s87, 1
	v_readlane_b32 s5, v254, 5
	s_cmp_ge_i32 s0, s5
	s_cbranch_scc1 .LBB0_856
	s_cmp_lg_u32 s87, 0
	s_cbranch_scc0 .LBB0_843
	v_readlane_b32 s4, v253, 29
	v_mov_b32_e32 v0, v192
	s_add_i32 s10, s4, 1
	s_waitcnt lgkmcnt(0)
	s_barrier
	s_nop 0
	v_cmp_eq_u32_e32 vcc, 0, v0
	s_and_saveexec_b64 s[4:5], vcc
	s_cbranch_execz .LBB0_842
	s_mov_b64 s[8:9], exec
	v_mbcnt_lo_u32_b32 v0, s8, 0
	v_mbcnt_hi_u32_b32 v0, s9, v0
	v_cmp_eq_u32_e32 vcc, 0, v0
	buffer_wbl2 sc1
	s_waitcnt vmcnt(0)
	s_and_saveexec_b64 s[6:7], vcc
	s_cbranch_execz .LBB0_836
	v_readlane_b32 s11, v254, 18
	s_lshl_b32 s11, s11, 2
	s_bcnt1_i32_b64 s8, s[8:9]
	v_mov_b32_e32 v1, s11
	v_mov_b32_e32 v2, s8
	global_atomic_add v1, v1, v2, s[38:39] offset:256 sc0
